# w2 GEMM: residual tile lines touched two K-iterations before the end of each unit (dword loads into a scratch VGPR) so the epilogue's residual loads hit the L2
# speedup vs baseline: 1.0017x; 1.0004x over previous
.LBB0_1633:
	s_cmpk_eq_i32 s25, 0x7a
	s_cbranch_scc0 .Lpf2_skip
	v_readfirstlane_b32 s10, v210
	v_readfirstlane_b32 s11, v211
	s_lshl_b32 vcc_lo, s1, 20
	s_add_u32 s10, s10, vcc_lo
	s_addc_u32 s11, s11, 0
	v_mbcnt_lo_u32_b32 v243, -1, 0
	v_mbcnt_hi_u32_b32 v243, -1, v243
	v_and_b32_e32 v253, 15, v243
	v_and_b32_e32 v243, 48, v243
	v_lshl_or_b32 v243, v253, 12, v243
	global_load_dword v253, v243, s[10:11]
	global_load_dword v253, v243, s[10:11] offset:256
	s_add_u32 s10, s10, 0x10000
	s_addc_u32 s11, s11, 0
	global_load_dword v253, v243, s[10:11]
	global_load_dword v253, v243, s[10:11] offset:256
	s_add_u32 s10, s10, 0x10000
	s_addc_u32 s11, s11, 0
	global_load_dword v253, v243, s[10:11]
	global_load_dword v253, v243, s[10:11] offset:256
	s_add_u32 s10, s10, 0x10000
	s_addc_u32 s11, s11, 0
	global_load_dword v253, v243, s[10:11]
	global_load_dword v253, v243, s[10:11] offset:256
	s_add_u32 s10, s10, 0x50000
	s_addc_u32 s11, s11, 0
	global_load_dword v253, v243, s[10:11]
	global_load_dword v253, v243, s[10:11] offset:256
	s_add_u32 s10, s10, 0x10000
	s_addc_u32 s11, s11, 0
	global_load_dword v253, v243, s[10:11]
	global_load_dword v253, v243, s[10:11] offset:256
	s_add_u32 s10, s10, 0x10000
	s_addc_u32 s11, s11, 0
	global_load_dword v253, v243, s[10:11]
	global_load_dword v253, v243, s[10:11] offset:256
	s_add_u32 s10, s10, 0x10000
	s_addc_u32 s11, s11, 0
	global_load_dword v253, v243, s[10:11]
	global_load_dword v253, v243, s[10:11] offset:256
